# v119 + masked attention units remapped for K/V reuse in L2 (3 heads of one kv head / consecutive q blocks per CU); placement-matched
# baseline (speedup 1.0000x reference)
; __device__ __forceinline__ void attn_unit(int uv, const float* sink_l, const bf16_t* P, bf16_t* Y, ATT_LAS unsigned char* lds, const float* rpb_l, const float* qn_l, const float* kn_l) {
;     ...
;     if (a.mode != 0 && nlat > 0) {
.LBB0_644:
	s_xor_b64 s[2:3], s[24:25], -1
	s_cmp_gt_i32 s71, 0
	s_cselect_b64 s[0:1], -1, 0
	s_and_b64 s[0:1], s[4:5], s[0:1]
	s_andn2_b64 vcc, exec, s[0:1]
	s_waitcnt lgkmcnt(0)
	s_cbranch_vccnz .LBB0_536
	s_branch .Lmk_entry
	s_nop 0
	s_nop 0
	s_nop 0
	s_nop 0
	s_nop 0
	s_nop 0
	s_nop 0
	s_nop 0
	s_nop 0
	s_nop 0
	s_nop 0
	s_nop 0
	s_nop 0
	s_nop 0
	s_nop 0
	s_nop 0
	s_nop 0
	s_nop 0
	s_nop 0
	s_nop 0
	s_nop 0
	s_nop 0
	s_nop 0
	s_nop 0
	s_nop 0
	s_nop 0
	s_nop 0
	s_nop 0
	s_nop 0
	s_nop 0
	s_nop 0
	s_nop 0
	s_nop 0
	s_nop 0
	s_nop 0
	s_nop 0
	s_nop 0
	s_nop 0
	s_nop 0
	s_nop 0
	s_nop 0
	s_nop 0
	s_nop 0
	s_nop 0
	s_nop 0
	s_nop 0
	s_nop 0
	s_nop 0
	s_nop 0
	s_nop 0
	s_nop 0
	s_nop 0
	s_nop 0
	s_nop 0
	s_nop 0
	s_nop 0
	s_nop 0
	s_nop 0
